# v52 + FF1 and G1 K-loops: load phases at priority 1, MFMA phases at priority 0
# baseline (speedup 1.0000x reference)
.LBB0_467:
	s_add_i32 s46, s42, 2
	s_add_u32 s47, s40, 0x80
	s_addc_u32 s43, s41, 0
	s_add_i32 s50, 0, 0x10000
	s_cmp_eq_u32 s75, s42
	s_cselect_b32 s43, s28, s43
	s_cselect_b32 s42, s29, s47
	v_add_u32_e32 v0, s50, v180
	s_cselect_b32 s49, s81, s45
	s_cselect_b32 s48, s80, s44
	s_add_i32 s47, 0, 0x14000
	ds_read_b128 v[130:133], v0
	ds_read_b128 v[134:137], v0 offset:1024
	ds_read_b128 v[138:141], v0 offset:2048
	ds_read_b128 v[142:145], v0 offset:3072
	v_add_u32_e32 v0, s47, v180
	ds_read_b128 v[158:161], v0
	ds_read_b128 v[162:165], v0 offset:1024
	ds_read_b128 v[166:169], v0 offset:2048
	ds_read_b128 v[170:173], v0 offset:3072
	v_lshl_add_u64 v[220:221], s[40:41], 0, v[152:153]
	s_mov_b32 m0, s27
	s_nop 0
	global_load_lds_dwordx4 v[220:221], off
	v_lshl_add_u64 v[220:221], s[40:41], 0, v[148:149]
	s_mov_b32 m0, s72
	s_nop 0
	global_load_lds_dwordx4 v[220:221], off
	v_lshl_add_u64 v[220:221], s[40:41], 0, v[154:155]
	s_add_i32 m0, s53, 0xc000
	s_nop 0
	global_load_lds_dwordx4 v[220:221], off
	v_lshl_add_u64 v[220:221], s[40:41], 0, v[156:157]
	s_add_i32 m0, s53, 0xe000
	s_nop 0
	global_load_lds_dwordx4 v[220:221], off
	ds_read_b128 v[174:177], v181
	ds_read_b128 v[182:185], v181 offset:1024
	ds_read_b128 v[186:189], v181 offset:2048
	ds_read_b128 v[200:203], v181 offset:3072
	ds_read_b128 v[204:207], v181 offset:4096
	ds_read_b128 v[208:211], v181 offset:5120
	ds_read_b128 v[212:215], v181 offset:6144
	ds_read_b128 v[216:219], v181 offset:7168
	s_waitcnt vmcnt(8)
	s_waitcnt lgkmcnt(0)
	s_barrier
	s_setprio 0
	s_waitcnt lgkmcnt(0)
	v_mfma_f32_16x16x32_bf16 v[126:129], v[130:133], v[174:177], v[126:129]
	v_mfma_f32_16x16x32_bf16 v[122:125], v[138:141], v[174:177], v[122:125]
	v_mfma_f32_16x16x32_bf16 v[110:113], v[130:133], v[186:189], v[110:113]
	v_mfma_f32_16x16x32_bf16 v[106:109], v[138:141], v[186:189], v[106:109]
	v_mfma_f32_16x16x32_bf16 v[94:97], v[130:133], v[204:207], v[94:97]
	v_mfma_f32_16x16x32_bf16 v[90:93], v[138:141], v[204:207], v[90:93]
	v_mfma_f32_16x16x32_bf16 v[78:81], v[130:133], v[212:215], v[78:81]
	v_mfma_f32_16x16x32_bf16 v[74:77], v[138:141], v[212:215], v[74:77]
	v_mfma_f32_16x16x32_bf16 v[126:129], v[134:137], v[182:185], v[126:129]
	v_mfma_f32_16x16x32_bf16 v[122:125], v[142:145], v[182:185], v[122:125]
	v_mfma_f32_16x16x32_bf16 v[110:113], v[134:137], v[200:203], v[110:113]
	v_mfma_f32_16x16x32_bf16 v[106:109], v[142:145], v[200:203], v[106:109]
	v_mfma_f32_16x16x32_bf16 v[94:97], v[134:137], v[208:211], v[94:97]
	v_mfma_f32_16x16x32_bf16 v[90:93], v[142:145], v[208:211], v[90:93]
	v_mfma_f32_16x16x32_bf16 v[78:81], v[134:137], v[216:219], v[78:81]
	v_mfma_f32_16x16x32_bf16 v[74:77], v[142:145], v[216:219], v[74:77]
	v_mfma_f32_16x16x32_bf16 v[118:121], v[158:161], v[174:177], v[118:121]
	v_mfma_f32_16x16x32_bf16 v[114:117], v[166:169], v[174:177], v[114:117]
	v_mfma_f32_16x16x32_bf16 v[102:105], v[158:161], v[186:189], v[102:105]
	v_mfma_f32_16x16x32_bf16 v[98:101], v[166:169], v[186:189], v[98:101]
	v_mfma_f32_16x16x32_bf16 v[86:89], v[158:161], v[204:207], v[86:89]
	v_mfma_f32_16x16x32_bf16 v[82:85], v[166:169], v[204:207], v[82:85]
	v_mfma_f32_16x16x32_bf16 v[70:73], v[158:161], v[212:215], v[70:73]
	v_mfma_f32_16x16x32_bf16 v[66:69], v[166:169], v[212:215], v[66:69]
	v_mfma_f32_16x16x32_bf16 v[118:121], v[162:165], v[182:185], v[118:121]
	v_mfma_f32_16x16x32_bf16 v[114:117], v[170:173], v[182:185], v[114:117]
	v_mfma_f32_16x16x32_bf16 v[102:105], v[162:165], v[200:203], v[102:105]
	v_mfma_f32_16x16x32_bf16 v[98:101], v[170:173], v[200:203], v[98:101]
	v_mfma_f32_16x16x32_bf16 v[86:89], v[162:165], v[208:211], v[86:89]
	v_mfma_f32_16x16x32_bf16 v[82:85], v[170:173], v[208:211], v[82:85]
	v_mfma_f32_16x16x32_bf16 v[70:73], v[162:165], v[216:219], v[70:73]
	v_mfma_f32_16x16x32_bf16 v[66:69], v[170:173], v[216:219], v[66:69]
	s_setprio 1
	s_barrier
	s_add_i32 s50, s50, s31
	v_lshl_add_u64 v[220:221], s[48:49], 0, v[150:151]
	s_mov_b32 m0, s50
	ds_read_b128 v[174:177], v181 offset:16384
	ds_read_b128 v[182:185], v181 offset:17408
	ds_read_b128 v[186:189], v181 offset:18432
	ds_read_b128 v[200:203], v181 offset:19456
	ds_read_b128 v[204:207], v181 offset:20480
	ds_read_b128 v[208:211], v181 offset:21504
	ds_read_b128 v[212:215], v181 offset:22528
	ds_read_b128 v[216:219], v181 offset:23552
	global_load_lds_dwordx4 v[220:221], off
	s_add_i32 m0, s50, 0x2000
	v_lshl_add_u64 v[222:223], s[48:49], 0, v[146:147]
	s_add_u32 s48, s48, s56
	s_addc_u32 s49, s49, s57
	s_add_i32 s47, s47, s31
	global_load_lds_dwordx4 v[222:223], off
	v_lshl_add_u64 v[224:225], s[48:49], 0, v[150:151]
	s_mov_b32 m0, s47
	v_lshl_add_u64 v[226:227], s[48:49], 0, v[146:147]
	global_load_lds_dwordx4 v[224:225], off
	s_add_i32 m0, s47, 0x2000
	v_lshl_add_u64 v[228:229], s[42:43], 0, v[152:153]
	global_load_lds_dwordx4 v[226:227], off
	v_lshl_add_u64 v[230:231], s[42:43], 0, v[148:149]
	s_waitcnt vmcnt(6)
	s_waitcnt lgkmcnt(0)
	s_barrier
	s_setprio 0
	s_waitcnt lgkmcnt(0)
	v_mfma_f32_16x16x32_bf16 v[62:65], v[130:133], v[174:177], v[62:65]
	v_mfma_f32_16x16x32_bf16 v[58:61], v[138:141], v[174:177], v[58:61]
	v_mfma_f32_16x16x32_bf16 v[46:49], v[130:133], v[186:189], v[46:49]
	v_mfma_f32_16x16x32_bf16 v[42:45], v[138:141], v[186:189], v[42:45]
	v_mfma_f32_16x16x32_bf16 v[30:33], v[130:133], v[204:207], v[30:33]
	v_mfma_f32_16x16x32_bf16 v[26:29], v[138:141], v[204:207], v[26:29]
	v_mfma_f32_16x16x32_bf16 v[14:17], v[130:133], v[212:215], v[14:17]
	v_mfma_f32_16x16x32_bf16 v[10:13], v[138:141], v[212:215], v[10:13]
	v_mfma_f32_16x16x32_bf16 v[62:65], v[134:137], v[182:185], v[62:65]
	v_mfma_f32_16x16x32_bf16 v[58:61], v[142:145], v[182:185], v[58:61]
	v_mfma_f32_16x16x32_bf16 v[46:49], v[134:137], v[200:203], v[46:49]
	v_mfma_f32_16x16x32_bf16 v[42:45], v[142:145], v[200:203], v[42:45]
	v_mfma_f32_16x16x32_bf16 v[30:33], v[134:137], v[208:211], v[30:33]
	v_mfma_f32_16x16x32_bf16 v[26:29], v[142:145], v[208:211], v[26:29]
	v_mfma_f32_16x16x32_bf16 v[14:17], v[134:137], v[216:219], v[14:17]
	v_mfma_f32_16x16x32_bf16 v[10:13], v[142:145], v[216:219], v[10:13]
	v_mfma_f32_16x16x32_bf16 v[54:57], v[158:161], v[174:177], v[54:57]
	v_mfma_f32_16x16x32_bf16 v[50:53], v[166:169], v[174:177], v[50:53]
	v_mfma_f32_16x16x32_bf16 v[38:41], v[158:161], v[186:189], v[38:41]
	v_mfma_f32_16x16x32_bf16 v[34:37], v[166:169], v[186:189], v[34:37]
	v_mfma_f32_16x16x32_bf16 v[22:25], v[158:161], v[204:207], v[22:25]
	v_mfma_f32_16x16x32_bf16 v[18:21], v[166:169], v[204:207], v[18:21]
	v_mfma_f32_16x16x32_bf16 v[6:9], v[158:161], v[212:215], v[6:9]
	v_mfma_f32_16x16x32_bf16 v[2:5], v[166:169], v[212:215], v[2:5]
	v_mfma_f32_16x16x32_bf16 v[54:57], v[162:165], v[182:185], v[54:57]
	v_mfma_f32_16x16x32_bf16 v[50:53], v[170:173], v[182:185], v[50:53]
	v_mfma_f32_16x16x32_bf16 v[38:41], v[162:165], v[200:203], v[38:41]
	v_mfma_f32_16x16x32_bf16 v[34:37], v[170:173], v[200:203], v[34:37]
	v_mfma_f32_16x16x32_bf16 v[22:25], v[162:165], v[208:211], v[22:25]
	v_mfma_f32_16x16x32_bf16 v[18:21], v[170:173], v[208:211], v[18:21]
	v_mfma_f32_16x16x32_bf16 v[6:9], v[162:165], v[216:219], v[6:9]
	v_mfma_f32_16x16x32_bf16 v[2:5], v[170:173], v[216:219], v[2:5]
	s_setprio 1
	s_barrier
	s_add_i32 s47, 0, 0x18000
	v_add_u32_e32 v0, s47, v180
	s_add_i32 s48, 0, 0x1c000
	ds_read_b128 v[130:133], v0
	ds_read_b128 v[134:137], v0 offset:1024
	ds_read_b128 v[138:141], v0 offset:2048
	ds_read_b128 v[142:145], v0 offset:3072
	v_add_u32_e32 v0, s48, v180
	ds_read_b128 v[158:161], v0
	ds_read_b128 v[162:165], v0 offset:1024
	ds_read_b128 v[166:169], v0 offset:2048
	ds_read_b128 v[170:173], v0 offset:3072
	s_add_u32 s42, s42, s54
	s_addc_u32 s43, s43, s55
	s_mov_b32 m0, s53
	v_lshl_add_u64 v[232:233], s[42:43], 0, v[152:153]
	s_nop 0
	global_load_lds_dwordx4 v[228:229], off
	s_mov_b32 m0, s4
	s_nop 0
	global_load_lds_dwordx4 v[230:231], off
	s_mov_b32 m0, s82
	s_nop 0
	global_load_lds_dwordx4 v[232:233], off
	v_lshl_add_u64 v[232:233], s[42:43], 0, v[148:149]
	s_mov_b32 m0, s83
	s_nop 0
	global_load_lds_dwordx4 v[232:233], off
	ds_read_b128 v[174:177], v181 offset:32768
	ds_read_b128 v[182:185], v181 offset:33792
	ds_read_b128 v[186:189], v181 offset:34816
	ds_read_b128 v[200:203], v181 offset:35840
	ds_read_b128 v[204:207], v181 offset:36864
	ds_read_b128 v[208:211], v181 offset:37888
	ds_read_b128 v[212:215], v181 offset:38912
	ds_read_b128 v[216:219], v181 offset:39936
	s_waitcnt vmcnt(8)
	s_waitcnt lgkmcnt(0)
	s_barrier
	s_setprio 0
	s_waitcnt lgkmcnt(0)
	v_mfma_f32_16x16x32_bf16 v[126:129], v[130:133], v[174:177], v[126:129]
	v_mfma_f32_16x16x32_bf16 v[122:125], v[138:141], v[174:177], v[122:125]
	v_mfma_f32_16x16x32_bf16 v[110:113], v[130:133], v[186:189], v[110:113]
	v_mfma_f32_16x16x32_bf16 v[106:109], v[138:141], v[186:189], v[106:109]
	v_mfma_f32_16x16x32_bf16 v[94:97], v[130:133], v[204:207], v[94:97]
	v_mfma_f32_16x16x32_bf16 v[90:93], v[138:141], v[204:207], v[90:93]
	v_mfma_f32_16x16x32_bf16 v[78:81], v[130:133], v[212:215], v[78:81]
	v_mfma_f32_16x16x32_bf16 v[74:77], v[138:141], v[212:215], v[74:77]
	v_mfma_f32_16x16x32_bf16 v[126:129], v[134:137], v[182:185], v[126:129]
	v_mfma_f32_16x16x32_bf16 v[122:125], v[142:145], v[182:185], v[122:125]
	v_mfma_f32_16x16x32_bf16 v[110:113], v[134:137], v[200:203], v[110:113]
	v_mfma_f32_16x16x32_bf16 v[106:109], v[142:145], v[200:203], v[106:109]
	v_mfma_f32_16x16x32_bf16 v[94:97], v[134:137], v[208:211], v[94:97]
	v_mfma_f32_16x16x32_bf16 v[90:93], v[142:145], v[208:211], v[90:93]
	v_mfma_f32_16x16x32_bf16 v[78:81], v[134:137], v[216:219], v[78:81]
	v_mfma_f32_16x16x32_bf16 v[74:77], v[142:145], v[216:219], v[74:77]
	v_mfma_f32_16x16x32_bf16 v[118:121], v[158:161], v[174:177], v[118:121]
	v_mfma_f32_16x16x32_bf16 v[114:117], v[166:169], v[174:177], v[114:117]
	v_mfma_f32_16x16x32_bf16 v[102:105], v[158:161], v[186:189], v[102:105]
	v_mfma_f32_16x16x32_bf16 v[98:101], v[166:169], v[186:189], v[98:101]
	v_mfma_f32_16x16x32_bf16 v[86:89], v[158:161], v[204:207], v[86:89]
	v_mfma_f32_16x16x32_bf16 v[82:85], v[166:169], v[204:207], v[82:85]
	v_mfma_f32_16x16x32_bf16 v[70:73], v[158:161], v[212:215], v[70:73]
	v_mfma_f32_16x16x32_bf16 v[66:69], v[166:169], v[212:215], v[66:69]
	v_mfma_f32_16x16x32_bf16 v[118:121], v[162:165], v[182:185], v[118:121]
	v_mfma_f32_16x16x32_bf16 v[114:117], v[170:173], v[182:185], v[114:117]
	v_mfma_f32_16x16x32_bf16 v[102:105], v[162:165], v[200:203], v[102:105]
	v_mfma_f32_16x16x32_bf16 v[98:101], v[170:173], v[200:203], v[98:101]
	v_mfma_f32_16x16x32_bf16 v[86:89], v[162:165], v[208:211], v[86:89]
	v_mfma_f32_16x16x32_bf16 v[82:85], v[170:173], v[208:211], v[82:85]
	v_mfma_f32_16x16x32_bf16 v[70:73], v[162:165], v[216:219], v[70:73]
	v_mfma_f32_16x16x32_bf16 v[66:69], v[170:173], v[216:219], v[66:69]
	s_setprio 1
	s_barrier
	s_add_i32 s42, s47, s31
	v_lshl_add_u64 v[220:221], v[220:221], 0, s[24:25]
	s_mov_b32 m0, s42
	ds_read_b128 v[174:177], v181 offset:49152
	ds_read_b128 v[182:185], v181 offset:50176
	ds_read_b128 v[186:189], v181 offset:51200
	ds_read_b128 v[200:203], v181 offset:52224
	ds_read_b128 v[204:207], v181 offset:53248
	ds_read_b128 v[208:211], v181 offset:54272
	ds_read_b128 v[212:215], v181 offset:55296
	ds_read_b128 v[216:219], v181 offset:56320
	global_load_lds_dwordx4 v[220:221], off
	v_lshl_add_u64 v[220:221], v[222:223], 0, s[24:25]
	s_add_i32 m0, s42, 0x2000
	s_add_i32 s42, s48, s31
	global_load_lds_dwordx4 v[220:221], off
	v_lshl_add_u64 v[220:221], v[224:225], 0, s[24:25]
	s_mov_b32 m0, s42
	s_nop 0
	global_load_lds_dwordx4 v[220:221], off
	v_lshl_add_u64 v[220:221], v[226:227], 0, s[24:25]
	s_add_i32 m0, s42, 0x2000
	s_nop 0
	global_load_lds_dwordx4 v[220:221], off
	s_waitcnt vmcnt(6)
	s_waitcnt lgkmcnt(0)
	s_barrier
	s_setprio 0
	s_waitcnt lgkmcnt(0)
	v_mfma_f32_16x16x32_bf16 v[62:65], v[130:133], v[174:177], v[62:65]
	v_mfma_f32_16x16x32_bf16 v[58:61], v[138:141], v[174:177], v[58:61]
	v_mfma_f32_16x16x32_bf16 v[46:49], v[130:133], v[186:189], v[46:49]
	v_mfma_f32_16x16x32_bf16 v[42:45], v[138:141], v[186:189], v[42:45]
	v_mfma_f32_16x16x32_bf16 v[30:33], v[130:133], v[204:207], v[30:33]
	v_mfma_f32_16x16x32_bf16 v[26:29], v[138:141], v[204:207], v[26:29]
	v_mfma_f32_16x16x32_bf16 v[14:17], v[130:133], v[212:215], v[14:17]
	v_mfma_f32_16x16x32_bf16 v[10:13], v[138:141], v[212:215], v[10:13]
	v_mfma_f32_16x16x32_bf16 v[62:65], v[134:137], v[182:185], v[62:65]
	v_mfma_f32_16x16x32_bf16 v[58:61], v[142:145], v[182:185], v[58:61]
	v_mfma_f32_16x16x32_bf16 v[46:49], v[134:137], v[200:203], v[46:49]
	v_mfma_f32_16x16x32_bf16 v[42:45], v[142:145], v[200:203], v[42:45]
	v_mfma_f32_16x16x32_bf16 v[30:33], v[134:137], v[208:211], v[30:33]
	v_mfma_f32_16x16x32_bf16 v[26:29], v[142:145], v[208:211], v[26:29]
	v_mfma_f32_16x16x32_bf16 v[14:17], v[134:137], v[216:219], v[14:17]
	v_mfma_f32_16x16x32_bf16 v[10:13], v[142:145], v[216:219], v[10:13]
	v_mfma_f32_16x16x32_bf16 v[54:57], v[158:161], v[174:177], v[54:57]
	v_mfma_f32_16x16x32_bf16 v[50:53], v[166:169], v[174:177], v[50:53]
	v_mfma_f32_16x16x32_bf16 v[38:41], v[158:161], v[186:189], v[38:41]
	v_mfma_f32_16x16x32_bf16 v[34:37], v[166:169], v[186:189], v[34:37]
	v_mfma_f32_16x16x32_bf16 v[22:25], v[158:161], v[204:207], v[22:25]
	v_mfma_f32_16x16x32_bf16 v[18:21], v[166:169], v[204:207], v[18:21]
	v_mfma_f32_16x16x32_bf16 v[6:9], v[158:161], v[212:215], v[6:9]
	v_mfma_f32_16x16x32_bf16 v[2:5], v[166:169], v[212:215], v[2:5]
	v_mfma_f32_16x16x32_bf16 v[54:57], v[162:165], v[182:185], v[54:57]
	v_mfma_f32_16x16x32_bf16 v[50:53], v[170:173], v[182:185], v[50:53]
	v_mfma_f32_16x16x32_bf16 v[38:41], v[162:165], v[200:203], v[38:41]
	v_mfma_f32_16x16x32_bf16 v[34:37], v[170:173], v[200:203], v[34:37]
	v_mfma_f32_16x16x32_bf16 v[22:25], v[162:165], v[208:211], v[22:25]
	v_mfma_f32_16x16x32_bf16 v[18:21], v[170:173], v[208:211], v[18:21]
	v_mfma_f32_16x16x32_bf16 v[6:9], v[162:165], v[216:219], v[6:9]
	v_mfma_f32_16x16x32_bf16 v[2:5], v[170:173], v[216:219], v[2:5]
	s_setprio 1
	s_barrier
	s_add_u32 s40, s40, 0x100
	s_addc_u32 s41, s41, 0
	s_add_u32 s44, s44, 0x100
	s_addc_u32 s45, s45, 0
	s_cmp_ge_i32 s46, s74
	s_mov_b32 s42, s46
	s_cbranch_scc0 .LBB0_467
